# prologue: weight transposes hand-rewritten with all 32 row loads of a block in flight; adaLN cond activation loads batched
# speedup vs baseline: 1.0058x; 1.0004x over previous
.LBB0_9:
	global_load_dword v26, v[6:7], off
	v_lshl_add_u64 v[6:7], v[6:7], 0, s[4:5]
	global_load_dword v27, v[6:7], off
	v_lshl_add_u64 v[6:7], v[6:7], 0, s[4:5]
	global_load_dword v28, v[6:7], off
	v_lshl_add_u64 v[6:7], v[6:7], 0, s[4:5]
	global_load_dword v29, v[6:7], off
	v_lshl_add_u64 v[6:7], v[6:7], 0, s[4:5]
	global_load_dword v30, v[6:7], off
	v_lshl_add_u64 v[6:7], v[6:7], 0, s[4:5]
	global_load_dword v31, v[6:7], off
	v_lshl_add_u64 v[6:7], v[6:7], 0, s[4:5]
	global_load_dword v32, v[6:7], off
	v_lshl_add_u64 v[6:7], v[6:7], 0, s[4:5]
	global_load_dword v33, v[6:7], off
	v_lshl_add_u64 v[6:7], v[6:7], 0, s[4:5]
	global_load_dword v34, v[6:7], off
	v_lshl_add_u64 v[6:7], v[6:7], 0, s[4:5]
	global_load_dword v35, v[6:7], off
	v_lshl_add_u64 v[6:7], v[6:7], 0, s[4:5]
	global_load_dword v36, v[6:7], off
	v_lshl_add_u64 v[6:7], v[6:7], 0, s[4:5]
	global_load_dword v37, v[6:7], off
	v_lshl_add_u64 v[6:7], v[6:7], 0, s[4:5]
	global_load_dword v38, v[6:7], off
	v_lshl_add_u64 v[6:7], v[6:7], 0, s[4:5]
	global_load_dword v39, v[6:7], off
	v_lshl_add_u64 v[6:7], v[6:7], 0, s[4:5]
	global_load_dword v40, v[6:7], off
	v_lshl_add_u64 v[6:7], v[6:7], 0, s[4:5]
	global_load_dword v41, v[6:7], off
	s_waitcnt vmcnt(15)
	v_mul_f32_e32 v11, 0xbfb8aa3b, v26
	v_exp_f32_e32 v11, v11
	s_nop 0
	v_add_f32_e32 v11, 1.0, v11
	v_rcp_f32_e32 v11, v11
	s_nop 0
	v_mul_f32_e32 v10, v26, v11
	ds_write_b32 v8, v10 offset:0
	s_waitcnt vmcnt(14)
	v_mul_f32_e32 v11, 0xbfb8aa3b, v27
	v_exp_f32_e32 v11, v11
	s_nop 0
	v_add_f32_e32 v11, 1.0, v11
	v_rcp_f32_e32 v11, v11
	s_nop 0
	v_mul_f32_e32 v10, v27, v11
	ds_write_b32 v8, v10 offset:2048
	s_waitcnt vmcnt(13)
	v_mul_f32_e32 v11, 0xbfb8aa3b, v28
	v_exp_f32_e32 v11, v11
	s_nop 0
	v_add_f32_e32 v11, 1.0, v11
	v_rcp_f32_e32 v11, v11
	s_nop 0
	v_mul_f32_e32 v10, v28, v11
	ds_write_b32 v8, v10 offset:4096
	s_waitcnt vmcnt(12)
	v_mul_f32_e32 v11, 0xbfb8aa3b, v29
	v_exp_f32_e32 v11, v11
	s_nop 0
	v_add_f32_e32 v11, 1.0, v11
	v_rcp_f32_e32 v11, v11
	s_nop 0
	v_mul_f32_e32 v10, v29, v11
	ds_write_b32 v8, v10 offset:6144
	s_waitcnt vmcnt(11)
	v_mul_f32_e32 v11, 0xbfb8aa3b, v30
	v_exp_f32_e32 v11, v11
	s_nop 0
	v_add_f32_e32 v11, 1.0, v11
	v_rcp_f32_e32 v11, v11
	s_nop 0
	v_mul_f32_e32 v10, v30, v11
	ds_write_b32 v8, v10 offset:8192
	s_waitcnt vmcnt(10)
	v_mul_f32_e32 v11, 0xbfb8aa3b, v31
	v_exp_f32_e32 v11, v11
	s_nop 0
	v_add_f32_e32 v11, 1.0, v11
	v_rcp_f32_e32 v11, v11
	s_nop 0
	v_mul_f32_e32 v10, v31, v11
	ds_write_b32 v8, v10 offset:10240
	s_waitcnt vmcnt(9)
	v_mul_f32_e32 v11, 0xbfb8aa3b, v32
	v_exp_f32_e32 v11, v11
	s_nop 0
	v_add_f32_e32 v11, 1.0, v11
	v_rcp_f32_e32 v11, v11
	s_nop 0
	v_mul_f32_e32 v10, v32, v11
	ds_write_b32 v8, v10 offset:12288
	s_waitcnt vmcnt(8)
	v_mul_f32_e32 v11, 0xbfb8aa3b, v33
	v_exp_f32_e32 v11, v11
	s_nop 0
	v_add_f32_e32 v11, 1.0, v11
	v_rcp_f32_e32 v11, v11
	s_nop 0
	v_mul_f32_e32 v10, v33, v11
	ds_write_b32 v8, v10 offset:14336
	s_waitcnt vmcnt(7)
	v_mul_f32_e32 v11, 0xbfb8aa3b, v34
	v_exp_f32_e32 v11, v11
	s_nop 0
	v_add_f32_e32 v11, 1.0, v11
	v_rcp_f32_e32 v11, v11
	s_nop 0
	v_mul_f32_e32 v10, v34, v11
	ds_write_b32 v8, v10 offset:16384
	s_waitcnt vmcnt(6)
	v_mul_f32_e32 v11, 0xbfb8aa3b, v35
	v_exp_f32_e32 v11, v11
	s_nop 0
	v_add_f32_e32 v11, 1.0, v11
	v_rcp_f32_e32 v11, v11
	s_nop 0
	v_mul_f32_e32 v10, v35, v11
	ds_write_b32 v8, v10 offset:18432
	s_waitcnt vmcnt(5)
	v_mul_f32_e32 v11, 0xbfb8aa3b, v36
	v_exp_f32_e32 v11, v11
	s_nop 0
	v_add_f32_e32 v11, 1.0, v11
	v_rcp_f32_e32 v11, v11
	s_nop 0
	v_mul_f32_e32 v10, v36, v11
	ds_write_b32 v8, v10 offset:20480
	s_waitcnt vmcnt(4)
	v_mul_f32_e32 v11, 0xbfb8aa3b, v37
	v_exp_f32_e32 v11, v11
	s_nop 0
	v_add_f32_e32 v11, 1.0, v11
	v_rcp_f32_e32 v11, v11
	s_nop 0
	v_mul_f32_e32 v10, v37, v11
	ds_write_b32 v8, v10 offset:22528
	s_waitcnt vmcnt(3)
	v_mul_f32_e32 v11, 0xbfb8aa3b, v38
	v_exp_f32_e32 v11, v11
	s_nop 0
	v_add_f32_e32 v11, 1.0, v11
	v_rcp_f32_e32 v11, v11
	s_nop 0
	v_mul_f32_e32 v10, v38, v11
	ds_write_b32 v8, v10 offset:24576
	s_waitcnt vmcnt(2)
	v_mul_f32_e32 v11, 0xbfb8aa3b, v39
	v_exp_f32_e32 v11, v11
	s_nop 0
	v_add_f32_e32 v11, 1.0, v11
	v_rcp_f32_e32 v11, v11
	s_nop 0
	v_mul_f32_e32 v10, v39, v11
	ds_write_b32 v8, v10 offset:26624
	s_waitcnt vmcnt(1)
	v_mul_f32_e32 v11, 0xbfb8aa3b, v40
	v_exp_f32_e32 v11, v11
	s_nop 0
	v_add_f32_e32 v11, 1.0, v11
	v_rcp_f32_e32 v11, v11
	s_nop 0
	v_mul_f32_e32 v10, v40, v11
	ds_write_b32 v8, v10 offset:28672
	s_waitcnt vmcnt(0)
	v_mul_f32_e32 v11, 0xbfb8aa3b, v41
	v_exp_f32_e32 v11, v11
	s_nop 0
	v_add_f32_e32 v11, 1.0, v11
	v_rcp_f32_e32 v11, v11
	s_nop 0
	v_mul_f32_e32 v10, v41, v11
	ds_write_b32 v8, v10 offset:30720

.LBB0_13:
	s_lshl_b32 s72, s28, 3
	s_add_i32 s29, s30, s72
	s_add_u32 s54, s22, 0x200000
	s_addc_u32 s55, s23, 0
	s_add_u32 s0, s22, 0x1a00000
	v_writelane_b32 v253, s0, 0
	s_addc_u32 s0, s23, 0
	v_writelane_b32 v253, s0, 1
	s_add_u32 s0, s22, 0x2200000
	v_writelane_b32 v253, s0, 2
	s_addc_u32 s0, s23, 0
	v_writelane_b32 v253, s0, 3
	s_add_u32 s0, s22, 0x2400000
	v_writelane_b32 v253, s0, 4
	s_addc_u32 s0, s23, 0
	v_writelane_b32 v253, s0, 5
	s_cmpk_gt_i32 s29, 0x227f
	s_cbranch_scc1 .LBB0_194
	s_waitcnt lgkmcnt(0)
	s_mul_i32 s0, s30, 0x2100
	s_add_i32 s0, s0, 0xc000
	s_lshl_b32 s38, s24, 3
	v_and_b32_e32 v3, 31, v64
	v_lshrrev_b32_e32 v4, 5, v64
	v_and_b32_e32 v5, 7, v64
	v_lshrrev_b32_e32 v6, 3, v64
	v_mul_u32_u24_e32 v7, 33, v4
	v_add_u32_e32 v7, v7, v3
	v_lshl_add_u32 v7, v7, 2, s0
	v_mul_u32_u24_e32 v8, 0x108, v5
	v_add_u32_e32 v8, v8, v6
	v_lshl_add_u32 v8, v8, 2, s0
	v_lshlrev_b32_e32 v13, 5, v5
.Ltr_loop:
	s_mul_hi_i32 s0, s29, 0x76b981db
	s_lshr_b32 s1, s0, 31
	s_ashr_i32 s0, s0, 10
	s_add_i32 s26, s0, s1
	s_mul_i32 s0, s26, 0xfffff760
	s_add_i32 s36, s29, s0
	s_mov_b64 s[40:41], exec
	s_cmpk_gt_i32 s36, 0x5ff
	s_cbranch_scc1 .Ltr_not_in
	s_mul_i32 s0, s36, 0x2ab
	s_lshr_b32 s0, s0, 16
	s_mul_i32 s1, s0, 0x60
	s_sub_i32 s1, s36, s1
	s_mul_i32 s27, s26, 0xba8000
	s_add_u32 s34, s68, s27
	s_addc_u32 s35, s69, 0
	s_mul_i32 s27, s0, 0xba800
	s_add_u32 s34, s34, s27
	s_addc_u32 s35, s35, 0
	s_movk_i32 s39, 0x5d40
	s_movk_i32 s42, 0xba8
	s_mul_i32 s27, s26, 0x600000
	s_add_u32 s36, s54, s27
	s_addc_u32 s37, s55, 0
	s_lshl_b32 s27, s1, 16
	s_add_u32 s36, s36, s27
	s_addc_u32 s37, s37, 0
	s_lshl_b32 s27, s0, 7
	s_add_u32 s36, s36, s27
	s_addc_u32 s37, s37, 0
	s_movk_i32 s7, 0x400
	s_movk_i32 s43, 0x4000
	s_mov_b32 s6, 0
	s_lshl_b32 s27, s1, 5
	v_add_u32_e32 v9, s27, v3
	v_add_u32_e32 v10, 8, v9
	v_cmp_gt_u32_e32 vcc, 0x600, v9
	s_nop 1
	v_cndmask_b32_e32 v10, v10, v9, vcc
	v_add_u32_e32 v11, 0xfffffa60, v9
	v_cmp_gt_u32_e32 vcc, 0xba0, v9
	s_nop 1
	v_cndmask_b32_e32 v10, v11, v10, vcc
	v_cmp_gt_u32_e32 vcc, 0xba8, v9
	s_nop 1
	v_cndmask_b32_e32 v10, 0, v10, vcc
	s_mov_b64 s[40:41], vcc
	s_branch .Ltr_go
.Ltr_not_in:
	s_cmpk_gt_i32 s36, 0x7ff
	s_cbranch_scc1 .Ltr_not_out
	s_add_i32 s36, s36, 0xfffffa00
	s_lshr_b32 s0, s36, 5
	s_and_b32 s1, s36, 31
	s_lshl_b32 s27, s26, 22
	s_add_u32 s34, s16, s27
	s_addc_u32 s35, s17, 0
	s_lshl_b32 s27, s0, 18
	s_add_u32 s34, s34, s27
	s_addc_u32 s35, s35, 0
	s_movk_i32 s39, 0x2000
	s_movk_i32 s42, 0x400
	s_lshl_b32 s27, s26, 21
	s_add_i32 s27, s27, 0x1a00000
	s_add_u32 s36, s22, s27
	s_addc_u32 s37, s23, 0
	s_lshl_b32 s27, s1, 16
	s_add_u32 s36, s36, s27
	s_addc_u32 s37, s37, 0
	s_lshl_b32 s27, s0, 7
	s_add_u32 s36, s36, s27
	s_addc_u32 s37, s37, 0
	s_movk_i32 s7, 0x400
	s_movk_i32 s43, 0x4000
	s_mov_b32 s6, 0
	s_lshl_b32 s27, s1, 5
	v_add_u32_e32 v10, s27, v3
	s_branch .Ltr_go
.Ltr_not_out:
	s_cmpk_gt_i32 s36, 0x85f
	s_cbranch_scc1 .Ltr_ukv
	s_add_i32 s36, s36, 0xfffff800
	s_mul_i32 s0, s36, 0xab
	s_lshr_b32 s0, s0, 12
	s_mul_i32 s1, s0, 24
	s_sub_i32 s1, s36, s1
	s_mul_i32 s27, s26, 0xc0000
	s_add_u32 s34, s10, s27
	s_addc_u32 s35, s11, 0
	s_mul_i32 s27, s0, 0x30000
	s_add_u32 s34, s34, s27
	s_addc_u32 s35, s35, 0
	s_movk_i32 s39, 0x1800
	s_movk_i32 s42, 0x300
	s_mul_i32 s27, s26, 0x60000
	s_add_i32 s27, s27, 0x2200000
	s_add_u32 s36, s22, s27
	s_addc_u32 s37, s23, 0
	s_lshl_b32 s27, s1, 14
	s_add_u32 s36, s36, s27
	s_addc_u32 s37, s37, 0
	s_lshl_b32 s27, s0, 7
	s_add_u32 s36, s36, s27
	s_addc_u32 s37, s37, 0
	s_movk_i32 s7, 0x100
	s_movk_i32 s43, 0x1000
	s_mov_b32 s6, 1
	s_lshl_b32 s27, s26, 10
	s_add_u32 s30, s8, s27
	s_addc_u32 s31, s9, 0
	s_lshl_b32 s27, s0, 8
	s_add_u32 s30, s30, s27
	s_addc_u32 s31, s31, 0
	s_lshl_b32 s27, s1, 5
	v_add_u32_e32 v10, s27, v3
	s_branch .Ltr_go
.Ltr_ukv:
	s_add_i32 s36, s36, 0xfffff7a0
	s_lshr_b32 s0, s36, 5
	s_and_b32 s1, s36, 31
	s_lshl_b32 s27, s26, 19
	s_add_u32 s34, s14, s27
	s_addc_u32 s35, s15, 0
	s_lshl_b32 s27, s0, 18
	s_add_u32 s34, s34, s27
	s_addc_u32 s35, s35, 0
	s_movk_i32 s39, 0x2000
	s_movk_i32 s42, 0x400
	s_lshl_b32 s27, s26, 18
	s_add_i32 s27, s27, 0x2400000
	s_add_u32 s36, s22, s27
	s_addc_u32 s37, s23, 0
	s_lshl_b32 s27, s1, 13
	s_add_u32 s36, s36, s27
	s_addc_u32 s37, s37, 0
	s_lshl_b32 s27, s0, 7
	s_add_u32 s36, s36, s27
	s_addc_u32 s37, s37, 0
	s_movk_i32 s7, 0x80
	s_movk_i32 s43, 0x800
	s_mov_b32 s6, 1
	s_lshl_b32 s27, s26, 9
	s_add_u32 s30, s12, s27
	s_addc_u32 s31, s13, 0
	s_lshl_b32 s27, s0, 8
	s_add_u32 s30, s30, s27
	s_addc_u32 s31, s31, 0
	s_lshl_b32 s27, s1, 5
	v_add_u32_e32 v10, s27, v3
.Ltr_go:
	v_mul_u32_u24_e32 v12, s42, v4
	v_add_lshl_u32 v9, v12, v10, 2
	v_mul_u32_u24_e32 v14, s7, v6
	v_lshl_add_u32 v14, v5, 3, v14
	v_lshlrev_b32_e32 v14, 1, v14
	s_cmp_eq_u32 s6, 0
	s_cbranch_scc1 .Ltr_noksc_ld
	global_load_dwordx4 v[52:55], v13, s[30:31]
	global_load_dwordx4 v[56:59], v13, s[30:31] offset:16
.Ltr_noksc_ld:
	global_load_dword v20, v9, s[34:35]
	s_add_u32 s34, s34, s39
	s_addc_u32 s35, s35, 0
	global_load_dword v21, v9, s[34:35]
	s_add_u32 s34, s34, s39
	s_addc_u32 s35, s35, 0
	global_load_dword v22, v9, s[34:35]
	s_add_u32 s34, s34, s39
	s_addc_u32 s35, s35, 0
	global_load_dword v23, v9, s[34:35]
	s_add_u32 s34, s34, s39
	s_addc_u32 s35, s35, 0
	global_load_dword v24, v9, s[34:35]
	s_add_u32 s34, s34, s39
	s_addc_u32 s35, s35, 0
	global_load_dword v25, v9, s[34:35]
	s_add_u32 s34, s34, s39
	s_addc_u32 s35, s35, 0
	global_load_dword v26, v9, s[34:35]
	s_add_u32 s34, s34, s39
	s_addc_u32 s35, s35, 0
	global_load_dword v27, v9, s[34:35]
	s_add_u32 s34, s34, s39
	s_addc_u32 s35, s35, 0
	global_load_dword v28, v9, s[34:35]
	s_add_u32 s34, s34, s39
	s_addc_u32 s35, s35, 0
	global_load_dword v29, v9, s[34:35]
	s_add_u32 s34, s34, s39
	s_addc_u32 s35, s35, 0
	global_load_dword v30, v9, s[34:35]
	s_add_u32 s34, s34, s39
	s_addc_u32 s35, s35, 0
	global_load_dword v31, v9, s[34:35]
	s_add_u32 s34, s34, s39
	s_addc_u32 s35, s35, 0
	global_load_dword v32, v9, s[34:35]
	s_add_u32 s34, s34, s39
	s_addc_u32 s35, s35, 0
	global_load_dword v33, v9, s[34:35]
	s_add_u32 s34, s34, s39
	s_addc_u32 s35, s35, 0
	global_load_dword v34, v9, s[34:35]
	s_add_u32 s34, s34, s39
	s_addc_u32 s35, s35, 0
	global_load_dword v35, v9, s[34:35]
	s_add_u32 s34, s34, s39
	s_addc_u32 s35, s35, 0
	global_load_dword v36, v9, s[34:35]
	s_add_u32 s34, s34, s39
	s_addc_u32 s35, s35, 0
	global_load_dword v37, v9, s[34:35]
	s_add_u32 s34, s34, s39
	s_addc_u32 s35, s35, 0
	global_load_dword v38, v9, s[34:35]
	s_add_u32 s34, s34, s39
	s_addc_u32 s35, s35, 0
	global_load_dword v39, v9, s[34:35]
	s_add_u32 s34, s34, s39
	s_addc_u32 s35, s35, 0
	global_load_dword v40, v9, s[34:35]
	s_add_u32 s34, s34, s39
	s_addc_u32 s35, s35, 0
	global_load_dword v41, v9, s[34:35]
	s_add_u32 s34, s34, s39
	s_addc_u32 s35, s35, 0
	global_load_dword v42, v9, s[34:35]
	s_add_u32 s34, s34, s39
	s_addc_u32 s35, s35, 0
	global_load_dword v43, v9, s[34:35]
	s_add_u32 s34, s34, s39
	s_addc_u32 s35, s35, 0
	global_load_dword v44, v9, s[34:35]
	s_add_u32 s34, s34, s39
	s_addc_u32 s35, s35, 0
	global_load_dword v45, v9, s[34:35]
	s_add_u32 s34, s34, s39
	s_addc_u32 s35, s35, 0
	global_load_dword v46, v9, s[34:35]
	s_add_u32 s34, s34, s39
	s_addc_u32 s35, s35, 0
	global_load_dword v47, v9, s[34:35]
	s_add_u32 s34, s34, s39
	s_addc_u32 s35, s35, 0
	global_load_dword v48, v9, s[34:35]
	s_add_u32 s34, s34, s39
	s_addc_u32 s35, s35, 0
	global_load_dword v49, v9, s[34:35]
	s_add_u32 s34, s34, s39
	s_addc_u32 s35, s35, 0
	global_load_dword v50, v9, s[34:35]
	s_add_u32 s34, s34, s39
	s_addc_u32 s35, s35, 0
	global_load_dword v51, v9, s[34:35]
	s_waitcnt vmcnt(31)
	v_cndmask_b32_e64 v20, 0, v20, s[40:41]
	ds_write_b32 v7, v20 offset:0
	s_waitcnt vmcnt(30)
	v_cndmask_b32_e64 v21, 0, v21, s[40:41]
	ds_write_b32 v7, v21 offset:264
	s_waitcnt vmcnt(29)
	v_cndmask_b32_e64 v22, 0, v22, s[40:41]
	ds_write_b32 v7, v22 offset:528
	s_waitcnt vmcnt(28)
	v_cndmask_b32_e64 v23, 0, v23, s[40:41]
	ds_write_b32 v7, v23 offset:792
	s_waitcnt vmcnt(27)
	v_cndmask_b32_e64 v24, 0, v24, s[40:41]
	ds_write_b32 v7, v24 offset:1056
	s_waitcnt vmcnt(26)
	v_cndmask_b32_e64 v25, 0, v25, s[40:41]
	ds_write_b32 v7, v25 offset:1320
	s_waitcnt vmcnt(25)
	v_cndmask_b32_e64 v26, 0, v26, s[40:41]
	ds_write_b32 v7, v26 offset:1584
	s_waitcnt vmcnt(24)
	v_cndmask_b32_e64 v27, 0, v27, s[40:41]
	ds_write_b32 v7, v27 offset:1848
	s_waitcnt vmcnt(23)
	v_cndmask_b32_e64 v28, 0, v28, s[40:41]
	ds_write_b32 v7, v28 offset:2112
	s_waitcnt vmcnt(22)
	v_cndmask_b32_e64 v29, 0, v29, s[40:41]
	ds_write_b32 v7, v29 offset:2376
	s_waitcnt vmcnt(21)
	v_cndmask_b32_e64 v30, 0, v30, s[40:41]
	ds_write_b32 v7, v30 offset:2640
	s_waitcnt vmcnt(20)
	v_cndmask_b32_e64 v31, 0, v31, s[40:41]
	ds_write_b32 v7, v31 offset:2904
	s_waitcnt vmcnt(19)
	v_cndmask_b32_e64 v32, 0, v32, s[40:41]
	ds_write_b32 v7, v32 offset:3168
	s_waitcnt vmcnt(18)
	v_cndmask_b32_e64 v33, 0, v33, s[40:41]
	ds_write_b32 v7, v33 offset:3432
	s_waitcnt vmcnt(17)
	v_cndmask_b32_e64 v34, 0, v34, s[40:41]
	ds_write_b32 v7, v34 offset:3696
	s_waitcnt vmcnt(16)
	v_cndmask_b32_e64 v35, 0, v35, s[40:41]
	ds_write_b32 v7, v35 offset:3960
	s_waitcnt vmcnt(15)
	v_cndmask_b32_e64 v36, 0, v36, s[40:41]
	ds_write_b32 v7, v36 offset:4224
	s_waitcnt vmcnt(14)
	v_cndmask_b32_e64 v37, 0, v37, s[40:41]
	ds_write_b32 v7, v37 offset:4488
	s_waitcnt vmcnt(13)
	v_cndmask_b32_e64 v38, 0, v38, s[40:41]
	ds_write_b32 v7, v38 offset:4752
	s_waitcnt vmcnt(12)
	v_cndmask_b32_e64 v39, 0, v39, s[40:41]
	ds_write_b32 v7, v39 offset:5016
	s_waitcnt vmcnt(11)
	v_cndmask_b32_e64 v40, 0, v40, s[40:41]
	ds_write_b32 v7, v40 offset:5280
	s_waitcnt vmcnt(10)
	v_cndmask_b32_e64 v41, 0, v41, s[40:41]
	ds_write_b32 v7, v41 offset:5544
	s_waitcnt vmcnt(9)
	v_cndmask_b32_e64 v42, 0, v42, s[40:41]
	ds_write_b32 v7, v42 offset:5808
	s_waitcnt vmcnt(8)
	v_cndmask_b32_e64 v43, 0, v43, s[40:41]
	ds_write_b32 v7, v43 offset:6072
	s_waitcnt vmcnt(7)
	v_cndmask_b32_e64 v44, 0, v44, s[40:41]
	ds_write_b32 v7, v44 offset:6336
	s_waitcnt vmcnt(6)
	v_cndmask_b32_e64 v45, 0, v45, s[40:41]
	ds_write_b32 v7, v45 offset:6600
	s_waitcnt vmcnt(5)
	v_cndmask_b32_e64 v46, 0, v46, s[40:41]
	ds_write_b32 v7, v46 offset:6864
	s_waitcnt vmcnt(4)
	v_cndmask_b32_e64 v47, 0, v47, s[40:41]
	ds_write_b32 v7, v47 offset:7128
	s_waitcnt vmcnt(3)
	v_cndmask_b32_e64 v48, 0, v48, s[40:41]
	ds_write_b32 v7, v48 offset:7392
	s_waitcnt vmcnt(2)
	v_cndmask_b32_e64 v49, 0, v49, s[40:41]
	ds_write_b32 v7, v49 offset:7656
	s_waitcnt vmcnt(1)
	v_cndmask_b32_e64 v50, 0, v50, s[40:41]
	ds_write_b32 v7, v50 offset:7920
	s_waitcnt vmcnt(0)
	v_cndmask_b32_e64 v51, 0, v51, s[40:41]
	ds_write_b32 v7, v51 offset:8184
	s_waitcnt lgkmcnt(0)
	ds_read2_b32 v[20:21], v8 offset0:0 offset1:33
	ds_read2_b32 v[22:23], v8 offset0:66 offset1:99
	ds_read2_b32 v[24:25], v8 offset0:132 offset1:165
	ds_read2_b32 v[26:27], v8 offset0:198 offset1:231
	ds_read2_b32 v[28:29], v8 offset0:8 offset1:41
	ds_read2_b32 v[30:31], v8 offset0:74 offset1:107
	ds_read2_b32 v[32:33], v8 offset0:140 offset1:173
	ds_read2_b32 v[34:35], v8 offset0:206 offset1:239
	ds_read2_b32 v[36:37], v8 offset0:16 offset1:49
	ds_read2_b32 v[38:39], v8 offset0:82 offset1:115
	ds_read2_b32 v[40:41], v8 offset0:148 offset1:181
	ds_read2_b32 v[42:43], v8 offset0:214 offset1:247
	ds_read2_b32 v[44:45], v8 offset0:24 offset1:57
	ds_read2_b32 v[46:47], v8 offset0:90 offset1:123
	ds_read2_b32 v[48:49], v8 offset0:156 offset1:189
	ds_read2_b32 v[50:51], v8 offset0:222 offset1:255
	s_cmp_eq_u32 s6, 0
	s_waitcnt lgkmcnt(0)
	s_cbranch_scc1 .Ltr_noksc_mul
	v_pk_mul_f32 v[20:21], v[20:21], v[52:53]
	v_pk_mul_f32 v[22:23], v[22:23], v[54:55]
	v_pk_mul_f32 v[24:25], v[24:25], v[56:57]
	v_pk_mul_f32 v[26:27], v[26:27], v[58:59]
	v_pk_mul_f32 v[28:29], v[28:29], v[52:53]
	v_pk_mul_f32 v[30:31], v[30:31], v[54:55]
	v_pk_mul_f32 v[32:33], v[32:33], v[56:57]
	v_pk_mul_f32 v[34:35], v[34:35], v[58:59]
	v_pk_mul_f32 v[36:37], v[36:37], v[52:53]
	v_pk_mul_f32 v[38:39], v[38:39], v[54:55]
	v_pk_mul_f32 v[40:41], v[40:41], v[56:57]
	v_pk_mul_f32 v[42:43], v[42:43], v[58:59]
	v_pk_mul_f32 v[44:45], v[44:45], v[52:53]
	v_pk_mul_f32 v[46:47], v[46:47], v[54:55]
	v_pk_mul_f32 v[48:49], v[48:49], v[56:57]
	v_pk_mul_f32 v[50:51], v[50:51], v[58:59]
.Ltr_noksc_mul:
	v_cvt_pk_bf16_f32 v60, v20, v21
	v_cvt_pk_bf16_f32 v61, v22, v23
	v_cvt_pk_bf16_f32 v62, v24, v25
	v_cvt_pk_bf16_f32 v63, v26, v27
	v_cvt_pk_bf16_f32 v64, v28, v29
	v_cvt_pk_bf16_f32 v65, v30, v31
	v_cvt_pk_bf16_f32 v66, v32, v33
	v_cvt_pk_bf16_f32 v67, v34, v35
	v_cvt_pk_bf16_f32 v68, v36, v37
	v_cvt_pk_bf16_f32 v69, v38, v39
	v_cvt_pk_bf16_f32 v70, v40, v41
	v_cvt_pk_bf16_f32 v71, v42, v43
	v_cvt_pk_bf16_f32 v72, v44, v45
	v_cvt_pk_bf16_f32 v73, v46, v47
	v_cvt_pk_bf16_f32 v74, v48, v49
	v_cvt_pk_bf16_f32 v75, v50, v51
	global_store_dwordx4 v14, v[60:63], s[36:37]
	s_add_u32 s36, s36, s43
	s_addc_u32 s37, s37, 0
	global_store_dwordx4 v14, v[64:67], s[36:37]
	s_add_u32 s36, s36, s43
	s_addc_u32 s37, s37, 0
	global_store_dwordx4 v14, v[68:71], s[36:37]
	s_add_u32 s36, s36, s43
	s_addc_u32 s37, s37, 0
	global_store_dwordx4 v14, v[72:75], s[36:37]
	s_add_i32 s29, s29, s38
	s_cmpk_lt_i32 s29, 0x2280
	s_cbranch_scc1 .Ltr_loop
